# last partial round of the SwiGLU and hybrid in-proj GEMMs spread over all XCDs (one tile per CU)
# speedup vs baseline: 1.0203x; 1.0132x over previous
;     ...
;   for (int it = 0;; it++) {
;     int tile;
;     if (nb == 512) tile = ((it * 8 + (bid & 7)) << 6) + (bid >> 3); else tile = it * nb + bid;
;     tile += tbeg;
;     if (tile >= MTX * ntn || tile >= tend) break;
;     int mt, nt;
;     if (tile < nfull) { const int b_ = tile / band, w_ = tile - b_ * band; nt = w_ >> 3; mt = b_ * 8 + (w_ & 7); }
;     else { const int w_ = tile - nfull; nt = w_ / MREM; mt = (MTX / 8) * 8 + (w_ - nt * MREM); }
;     const int m0 = mt * BM, n0 = nt * 128;
.LBB0_2189:
	s_lshl_b32 s4, s8, 9
	s_add_i32 s7, s2, s4
	s_cmp_eq_u32 s8, 7
	s_cbranch_scc0 .Lhy_notail
	v_readlane_b32 s5, v244, 27
	s_lshr_b32 s4, s5, 3
	s_and_b32 s5, s5, 7
	s_lshl_b32 s7, s4, 3
	s_add_i32 s7, s7, s5
	s_add_i32 s7, s7, 0xe00
.Lhy_notail:
	s_cmpk_gt_i32 s7, 0xeb9
	s_mov_b64 s[4:5], -1
	s_cbranch_scc1 .LBB0_2184
.LBB0_2190:
	s_cmpk_gt_i32 s7, 0xe7f
	s_cbranch_scc0 .LBB0_2192
	s_add_i32 s4, s7, 0xfffff180
	s_lshr_b32 s6, s4, 1
	s_and_b32 s4, s7, 1
	s_or_b32 s9, s4, 0x80
	s_mov_b64 s[4:5], 0

;     ...
;   for (int it = 0;; it++) {
;     int tile;
;     if (nb == 512) tile = ((it * 8 + (bid & 7)) << 6) + (bid >> 3); else tile = it * nb + bid;
;     tile += tbeg;
;     if (tile >= MTX * ntn || tile >= tend) break;
;     int mt, nt;
;     if (tile < nfull) { const int b_ = tile / band, w_ = tile - b_ * band; nt = w_ >> 3; mt = b_ * 8 + (w_ & 7); }
;     else { const int w_ = tile - nfull; nt = w_ / MREM; mt = (MTX / 8) * 8 + (w_ - nt * MREM); }
;     const int m0 = mt * BM, n0 = nt * 128;
.LBB0_2620:
	s_lshl_b32 s4, s6, 9
	s_add_i32 s7, s2, s4
	s_cmp_eq_u32 s6, 11
	s_cbranch_scc0 .Lsw_notail
	v_readlane_b32 s5, v244, 27
	s_lshr_b32 s4, s5, 3
	s_and_b32 s5, s5, 7
	s_lshl_b32 s7, s4, 3
	s_add_i32 s7, s7, s5
	s_add_i32 s7, s7, 0x1600
	s_cmp_lt_u32 s4, 11
	s_cbranch_scc1 .Lsw_notail
	s_movk_i32 s7, 0x7fff
.Lsw_notail:
	s_cmpk_gt_i32 s7, 0x1657
	s_mov_b64 s[4:5], -1
	s_cbranch_scc1 .LBB0_2615
.LBB0_2621:
	s_cmpk_gt_i32 s7, 0x15ff
	s_cbranch_scc0 .LBB0_2623
	s_add_i32 s4, s7, 0xffffea00
	s_lshr_b32 s8, s4, 1
	s_and_b32 s4, s7, 1
	s_or_b32 s9, s4, 0x80
	s_mov_b64 s[4:5], 0
